# loop exit: one of the two s_nop 7 before the row-sum fold removed (one already covers the MFMA result distance)
# baseline (speedup 1.0000x reference)
; DI float red4_sum(float v, int lane) { v += lane_get(v, lane ^ 16); v += lane_get(v, lane ^ 32); return v; }
; DI void attn_phase(const Params& p, const int layer, const int wid_s) {
;     ...
;         if (br == 1) {
; #pragma unroll
;           for (int hp = 0; hp < 2; ++hp) {
;             const float lt = red4_sum(l[hp], lane);
;             const float sc = lt > 0.f ? gate[hp][1] / lt : 0.f;
; #pragma unroll
;             for (int dt = 0; dt < 4; ++dt)
; #pragma unroll
;               for (int j = 0; j < 4; ++j) fin[(hp * 16 + dt * 4 + j) * 64] += O[hp][dt][j] * sc;
;           }
.Lat_done:
	s_nop 7
	v_add_f32_e32 v214, v214, v215
	v_add_f32_e32 v216, v216, v217
	v_add_f32_e32 v218, v218, v219
	v_add_f32_e32 v220, v220, v221
	v_add_f32_e32 v2, v214, v216
	v_add_f32_e32 v3, v218, v220
	v_mov_b32_e32 v64, v60
	v_mov_b32_e32 v65, v61
	v_mov_b32_e32 v66, v62
	v_mov_b32_e32 v67, v63
	s_branch .LBB0_368
